# ev_in/odin bf16 staging: adjacent lanes exchange halves via DPP + v_perm so each lane writes one dword; 32 ds_write_b32 per tile instead of 64 ds_write_b16
# speedup vs baseline: 1.0045x; 1.0045x over previous
.Levin1_notr:
	s_cmp_eq_u32 s24, 2
	s_cbranch_scc1 .LBB0_259
	s_cmp_eq_u32 s24, 7
	s_cbranch_scc1 .LBB0_259
	s_cmp_ge_u32 s24, 3
	s_cselect_b32 s2, 1, 0
	s_sub_u32 s2, s24, s2
	s_cmp_ge_u32 s24, 8
	s_cselect_b32 s3, 1, 0
	s_sub_u32 s2, s2, s3
	s_lshl_b32 s2, s2, 9
	s_add_u32 s2, s2, s0
	s_lshl_b32 s2, s2, 1
	s_mul_i32 s3, s1, 0x1c00
	s_add_u32 s2, s2, s3
	s_add_u32 s98, s90, 0x3971900
	s_addc_u32 s99, s91, 0
	s_add_u32 s98, s98, s2
	s_addc_u32 s99, s99, 0
	v_and_b32_e32 v120, 1, v118
	v_lshlrev_b32_e32 v121, 6, v120
	v_sub_u32_e32 v121, v121, v120
	v_sub_u32_e32 v121, v121, v120
	v_add_u32_e32 v121, v121, v112
	v_cmp_eq_u32_e32 vcc, 1, v120
	v_mov_b32_e32 v120, 0x05040100
	v_mov_b32_e32 v122, 0x03020706
	s_nop 1
	v_cndmask_b32_e32 v120, v120, v122, vcc
	v_cvt_pk_bf16_f32 v64, v48, v49
	v_cvt_pk_bf16_f32 v65, v50, v51
	v_cvt_pk_bf16_f32 v66, v52, v53
	v_cvt_pk_bf16_f32 v67, v54, v55
	v_cvt_pk_bf16_f32 v68, v56, v57
	v_cvt_pk_bf16_f32 v69, v58, v59
	v_cvt_pk_bf16_f32 v70, v60, v61
	v_cvt_pk_bf16_f32 v71, v62, v63
	v_mov_b32_dpp v72, v64 quad_perm:[1,0,3,2] row_mask:0xf bank_mask:0xf
	v_mov_b32_dpp v73, v65 quad_perm:[1,0,3,2] row_mask:0xf bank_mask:0xf
	v_mov_b32_dpp v74, v66 quad_perm:[1,0,3,2] row_mask:0xf bank_mask:0xf
	v_mov_b32_dpp v75, v67 quad_perm:[1,0,3,2] row_mask:0xf bank_mask:0xf
	v_mov_b32_dpp v76, v68 quad_perm:[1,0,3,2] row_mask:0xf bank_mask:0xf
	v_mov_b32_dpp v77, v69 quad_perm:[1,0,3,2] row_mask:0xf bank_mask:0xf
	v_mov_b32_dpp v78, v70 quad_perm:[1,0,3,2] row_mask:0xf bank_mask:0xf
	v_mov_b32_dpp v79, v71 quad_perm:[1,0,3,2] row_mask:0xf bank_mask:0xf
	v_perm_b32 v72, v72, v64, v120
	v_perm_b32 v73, v73, v65, v120
	v_perm_b32 v74, v74, v66, v120
	v_perm_b32 v75, v75, v67, v120
	v_perm_b32 v76, v76, v68, v120
	v_perm_b32 v77, v77, v69, v120
	v_perm_b32 v78, v78, v70, v120
	v_perm_b32 v79, v79, v71, v120
	ds_write_b32 v121, v72
	ds_write_b32 v121, v73 offset:128
	ds_write_b32 v121, v74 offset:512
	ds_write_b32 v121, v75 offset:640
	ds_write_b32 v121, v76 offset:1024
	ds_write_b32 v121, v77 offset:1152
	ds_write_b32 v121, v78 offset:1536
	ds_write_b32 v121, v79 offset:1664
	ds_read_b128 v[80:83], v113
	ds_read_b128 v[84:87], v113 offset:1024
	v_cvt_pk_bf16_f32 v64, v16, v17
	v_cvt_pk_bf16_f32 v65, v18, v19
	v_cvt_pk_bf16_f32 v66, v20, v21
	v_cvt_pk_bf16_f32 v67, v22, v23
	v_cvt_pk_bf16_f32 v68, v24, v25
	v_cvt_pk_bf16_f32 v69, v26, v27
	v_cvt_pk_bf16_f32 v70, v28, v29
	v_cvt_pk_bf16_f32 v71, v30, v31
	v_mov_b32_dpp v72, v64 quad_perm:[1,0,3,2] row_mask:0xf bank_mask:0xf
	v_mov_b32_dpp v73, v65 quad_perm:[1,0,3,2] row_mask:0xf bank_mask:0xf
	v_mov_b32_dpp v74, v66 quad_perm:[1,0,3,2] row_mask:0xf bank_mask:0xf
	v_mov_b32_dpp v75, v67 quad_perm:[1,0,3,2] row_mask:0xf bank_mask:0xf
	v_mov_b32_dpp v76, v68 quad_perm:[1,0,3,2] row_mask:0xf bank_mask:0xf
	v_mov_b32_dpp v77, v69 quad_perm:[1,0,3,2] row_mask:0xf bank_mask:0xf
	v_mov_b32_dpp v78, v70 quad_perm:[1,0,3,2] row_mask:0xf bank_mask:0xf
	v_mov_b32_dpp v79, v71 quad_perm:[1,0,3,2] row_mask:0xf bank_mask:0xf
	v_perm_b32 v72, v72, v64, v120
	v_perm_b32 v73, v73, v65, v120
	v_perm_b32 v74, v74, v66, v120
	v_perm_b32 v75, v75, v67, v120
	v_perm_b32 v76, v76, v68, v120
	v_perm_b32 v77, v77, v69, v120
	v_perm_b32 v78, v78, v70, v120
	v_perm_b32 v79, v79, v71, v120
	ds_write_b32 v121, v72
	ds_write_b32 v121, v73 offset:128
	ds_write_b32 v121, v74 offset:512
	ds_write_b32 v121, v75 offset:640
	ds_write_b32 v121, v76 offset:1024
	ds_write_b32 v121, v77 offset:1152
	ds_write_b32 v121, v78 offset:1536
	ds_write_b32 v121, v79 offset:1664
	ds_read_b128 v[88:91], v113
	ds_read_b128 v[92:95], v113 offset:1024
	v_cvt_pk_bf16_f32 v64, v32, v33
	v_cvt_pk_bf16_f32 v65, v34, v35
	v_cvt_pk_bf16_f32 v66, v36, v37
	v_cvt_pk_bf16_f32 v67, v38, v39
	v_cvt_pk_bf16_f32 v68, v40, v41
	v_cvt_pk_bf16_f32 v69, v42, v43
	v_cvt_pk_bf16_f32 v70, v44, v45
	v_cvt_pk_bf16_f32 v71, v46, v47
	v_mov_b32_dpp v72, v64 quad_perm:[1,0,3,2] row_mask:0xf bank_mask:0xf
	v_mov_b32_dpp v73, v65 quad_perm:[1,0,3,2] row_mask:0xf bank_mask:0xf
	v_mov_b32_dpp v74, v66 quad_perm:[1,0,3,2] row_mask:0xf bank_mask:0xf
	v_mov_b32_dpp v75, v67 quad_perm:[1,0,3,2] row_mask:0xf bank_mask:0xf
	v_mov_b32_dpp v76, v68 quad_perm:[1,0,3,2] row_mask:0xf bank_mask:0xf
	v_mov_b32_dpp v77, v69 quad_perm:[1,0,3,2] row_mask:0xf bank_mask:0xf
	v_mov_b32_dpp v78, v70 quad_perm:[1,0,3,2] row_mask:0xf bank_mask:0xf
	v_mov_b32_dpp v79, v71 quad_perm:[1,0,3,2] row_mask:0xf bank_mask:0xf
	v_perm_b32 v72, v72, v64, v120
	v_perm_b32 v73, v73, v65, v120
	v_perm_b32 v74, v74, v66, v120
	v_perm_b32 v75, v75, v67, v120
	v_perm_b32 v76, v76, v68, v120
	v_perm_b32 v77, v77, v69, v120
	v_perm_b32 v78, v78, v70, v120
	v_perm_b32 v79, v79, v71, v120
	ds_write_b32 v121, v72
	ds_write_b32 v121, v73 offset:128
	ds_write_b32 v121, v74 offset:512
	ds_write_b32 v121, v75 offset:640
	ds_write_b32 v121, v76 offset:1024
	ds_write_b32 v121, v77 offset:1152
	ds_write_b32 v121, v78 offset:1536
	ds_write_b32 v121, v79 offset:1664
	ds_read_b128 v[96:99], v113
	ds_read_b128 v[100:103], v113 offset:1024
	v_cvt_pk_bf16_f32 v64, v0, v1
	v_cvt_pk_bf16_f32 v65, v2, v3
	v_cvt_pk_bf16_f32 v66, v4, v5
	v_cvt_pk_bf16_f32 v67, v6, v7
	v_cvt_pk_bf16_f32 v68, v8, v9
	v_cvt_pk_bf16_f32 v69, v10, v11
	v_cvt_pk_bf16_f32 v70, v12, v13
	v_cvt_pk_bf16_f32 v71, v14, v15
	v_mov_b32_dpp v72, v64 quad_perm:[1,0,3,2] row_mask:0xf bank_mask:0xf
	v_mov_b32_dpp v73, v65 quad_perm:[1,0,3,2] row_mask:0xf bank_mask:0xf
	v_mov_b32_dpp v74, v66 quad_perm:[1,0,3,2] row_mask:0xf bank_mask:0xf
	v_mov_b32_dpp v75, v67 quad_perm:[1,0,3,2] row_mask:0xf bank_mask:0xf
	v_mov_b32_dpp v76, v68 quad_perm:[1,0,3,2] row_mask:0xf bank_mask:0xf
	v_mov_b32_dpp v77, v69 quad_perm:[1,0,3,2] row_mask:0xf bank_mask:0xf
	v_mov_b32_dpp v78, v70 quad_perm:[1,0,3,2] row_mask:0xf bank_mask:0xf
	v_mov_b32_dpp v79, v71 quad_perm:[1,0,3,2] row_mask:0xf bank_mask:0xf
	v_perm_b32 v72, v72, v64, v120
	v_perm_b32 v73, v73, v65, v120
	v_perm_b32 v74, v74, v66, v120
	v_perm_b32 v75, v75, v67, v120
	v_perm_b32 v76, v76, v68, v120
	v_perm_b32 v77, v77, v69, v120
	v_perm_b32 v78, v78, v70, v120
	v_perm_b32 v79, v79, v71, v120
	ds_write_b32 v121, v72
	ds_write_b32 v121, v73 offset:128
	ds_write_b32 v121, v74 offset:512
	ds_write_b32 v121, v75 offset:640
	ds_write_b32 v121, v76 offset:1024
	ds_write_b32 v121, v77 offset:1152
	ds_write_b32 v121, v78 offset:1536
	ds_write_b32 v121, v79 offset:1664
	ds_read_b128 v[104:107], v113
	ds_read_b128 v[108:111], v113 offset:1024
	s_waitcnt lgkmcnt(0)
	global_store_dwordx4 v114, v[80:83], s[98:99]
	s_add_u32 s100, s98, 0x1c000
	s_addc_u32 s101, s99, 0
	global_store_dwordx4 v114, v[84:87], s[100:101]
	global_store_dwordx4 v114, v[88:91], s[98:99] offset:64
	global_store_dwordx4 v114, v[92:95], s[100:101] offset:64
	s_add_u32 s98, s98, 0x38000
	s_addc_u32 s99, s99, 0
	global_store_dwordx4 v114, v[96:99], s[98:99]
	s_add_u32 s100, s98, 0x1c000
	s_addc_u32 s101, s99, 0
	global_store_dwordx4 v114, v[100:103], s[100:101]
	global_store_dwordx4 v114, v[104:107], s[98:99] offset:64
	global_store_dwordx4 v114, v[108:111], s[100:101] offset:64
	s_branch .LBB0_259

.Lodin4_nat:
	s_lshl_b32 s8, s7, 11
	s_add_u32 s8, s8, s9
	s_lshl_b32 s9, s6, 1
	s_add_u32 s8, s8, s9
	s_add_u32 s98, s90, s8
	s_addc_u32 s99, s91, 0
	v_and_b32_e32 v120, 1, v118
	v_lshlrev_b32_e32 v121, 6, v120
	v_sub_u32_e32 v121, v121, v120
	v_sub_u32_e32 v121, v121, v120
	v_add_u32_e32 v121, v121, v112
	v_cmp_eq_u32_e32 vcc, 1, v120
	v_mov_b32_e32 v120, 0x05040100
	v_mov_b32_e32 v122, 0x03020706
	s_nop 1
	v_cndmask_b32_e32 v120, v120, v122, vcc
	v_cvt_pk_bf16_f32 v64, v48, v49
	v_cvt_pk_bf16_f32 v65, v50, v51
	v_cvt_pk_bf16_f32 v66, v52, v53
	v_cvt_pk_bf16_f32 v67, v54, v55
	v_cvt_pk_bf16_f32 v68, v56, v57
	v_cvt_pk_bf16_f32 v69, v58, v59
	v_cvt_pk_bf16_f32 v70, v60, v61
	v_cvt_pk_bf16_f32 v71, v62, v63
	v_mov_b32_dpp v72, v64 quad_perm:[1,0,3,2] row_mask:0xf bank_mask:0xf
	v_mov_b32_dpp v73, v65 quad_perm:[1,0,3,2] row_mask:0xf bank_mask:0xf
	v_mov_b32_dpp v74, v66 quad_perm:[1,0,3,2] row_mask:0xf bank_mask:0xf
	v_mov_b32_dpp v75, v67 quad_perm:[1,0,3,2] row_mask:0xf bank_mask:0xf
	v_mov_b32_dpp v76, v68 quad_perm:[1,0,3,2] row_mask:0xf bank_mask:0xf
	v_mov_b32_dpp v77, v69 quad_perm:[1,0,3,2] row_mask:0xf bank_mask:0xf
	v_mov_b32_dpp v78, v70 quad_perm:[1,0,3,2] row_mask:0xf bank_mask:0xf
	v_mov_b32_dpp v79, v71 quad_perm:[1,0,3,2] row_mask:0xf bank_mask:0xf
	v_perm_b32 v72, v72, v64, v120
	v_perm_b32 v73, v73, v65, v120
	v_perm_b32 v74, v74, v66, v120
	v_perm_b32 v75, v75, v67, v120
	v_perm_b32 v76, v76, v68, v120
	v_perm_b32 v77, v77, v69, v120
	v_perm_b32 v78, v78, v70, v120
	v_perm_b32 v79, v79, v71, v120
	ds_write_b32 v121, v72
	ds_write_b32 v121, v73 offset:128
	ds_write_b32 v121, v74 offset:512
	ds_write_b32 v121, v75 offset:640
	ds_write_b32 v121, v76 offset:1024
	ds_write_b32 v121, v77 offset:1152
	ds_write_b32 v121, v78 offset:1536
	ds_write_b32 v121, v79 offset:1664
	ds_read_b128 v[80:83], v113
	ds_read_b128 v[84:87], v113 offset:1024
	v_cvt_pk_bf16_f32 v64, v16, v17
	v_cvt_pk_bf16_f32 v65, v18, v19
	v_cvt_pk_bf16_f32 v66, v20, v21
	v_cvt_pk_bf16_f32 v67, v22, v23
	v_cvt_pk_bf16_f32 v68, v24, v25
	v_cvt_pk_bf16_f32 v69, v26, v27
	v_cvt_pk_bf16_f32 v70, v28, v29
	v_cvt_pk_bf16_f32 v71, v30, v31
	v_mov_b32_dpp v72, v64 quad_perm:[1,0,3,2] row_mask:0xf bank_mask:0xf
	v_mov_b32_dpp v73, v65 quad_perm:[1,0,3,2] row_mask:0xf bank_mask:0xf
	v_mov_b32_dpp v74, v66 quad_perm:[1,0,3,2] row_mask:0xf bank_mask:0xf
	v_mov_b32_dpp v75, v67 quad_perm:[1,0,3,2] row_mask:0xf bank_mask:0xf
	v_mov_b32_dpp v76, v68 quad_perm:[1,0,3,2] row_mask:0xf bank_mask:0xf
	v_mov_b32_dpp v77, v69 quad_perm:[1,0,3,2] row_mask:0xf bank_mask:0xf
	v_mov_b32_dpp v78, v70 quad_perm:[1,0,3,2] row_mask:0xf bank_mask:0xf
	v_mov_b32_dpp v79, v71 quad_perm:[1,0,3,2] row_mask:0xf bank_mask:0xf
	v_perm_b32 v72, v72, v64, v120
	v_perm_b32 v73, v73, v65, v120
	v_perm_b32 v74, v74, v66, v120
	v_perm_b32 v75, v75, v67, v120
	v_perm_b32 v76, v76, v68, v120
	v_perm_b32 v77, v77, v69, v120
	v_perm_b32 v78, v78, v70, v120
	v_perm_b32 v79, v79, v71, v120
	ds_write_b32 v121, v72
	ds_write_b32 v121, v73 offset:128
	ds_write_b32 v121, v74 offset:512
	ds_write_b32 v121, v75 offset:640
	ds_write_b32 v121, v76 offset:1024
	ds_write_b32 v121, v77 offset:1152
	ds_write_b32 v121, v78 offset:1536
	ds_write_b32 v121, v79 offset:1664
	ds_read_b128 v[88:91], v113
	ds_read_b128 v[92:95], v113 offset:1024
	v_cvt_pk_bf16_f32 v64, v32, v33
	v_cvt_pk_bf16_f32 v65, v34, v35
	v_cvt_pk_bf16_f32 v66, v36, v37
	v_cvt_pk_bf16_f32 v67, v38, v39
	v_cvt_pk_bf16_f32 v68, v40, v41
	v_cvt_pk_bf16_f32 v69, v42, v43
	v_cvt_pk_bf16_f32 v70, v44, v45
	v_cvt_pk_bf16_f32 v71, v46, v47
	v_mov_b32_dpp v72, v64 quad_perm:[1,0,3,2] row_mask:0xf bank_mask:0xf
	v_mov_b32_dpp v73, v65 quad_perm:[1,0,3,2] row_mask:0xf bank_mask:0xf
	v_mov_b32_dpp v74, v66 quad_perm:[1,0,3,2] row_mask:0xf bank_mask:0xf
	v_mov_b32_dpp v75, v67 quad_perm:[1,0,3,2] row_mask:0xf bank_mask:0xf
	v_mov_b32_dpp v76, v68 quad_perm:[1,0,3,2] row_mask:0xf bank_mask:0xf
	v_mov_b32_dpp v77, v69 quad_perm:[1,0,3,2] row_mask:0xf bank_mask:0xf
	v_mov_b32_dpp v78, v70 quad_perm:[1,0,3,2] row_mask:0xf bank_mask:0xf
	v_mov_b32_dpp v79, v71 quad_perm:[1,0,3,2] row_mask:0xf bank_mask:0xf
	v_perm_b32 v72, v72, v64, v120
	v_perm_b32 v73, v73, v65, v120
	v_perm_b32 v74, v74, v66, v120
	v_perm_b32 v75, v75, v67, v120
	v_perm_b32 v76, v76, v68, v120
	v_perm_b32 v77, v77, v69, v120
	v_perm_b32 v78, v78, v70, v120
	v_perm_b32 v79, v79, v71, v120
	ds_write_b32 v121, v72
	ds_write_b32 v121, v73 offset:128
	ds_write_b32 v121, v74 offset:512
	ds_write_b32 v121, v75 offset:640
	ds_write_b32 v121, v76 offset:1024
	ds_write_b32 v121, v77 offset:1152
	ds_write_b32 v121, v78 offset:1536
	ds_write_b32 v121, v79 offset:1664
	ds_read_b128 v[96:99], v113
	ds_read_b128 v[100:103], v113 offset:1024
	v_cvt_pk_bf16_f32 v64, v0, v1
	v_cvt_pk_bf16_f32 v65, v2, v3
	v_cvt_pk_bf16_f32 v66, v4, v5
	v_cvt_pk_bf16_f32 v67, v6, v7
	v_cvt_pk_bf16_f32 v68, v8, v9
	v_cvt_pk_bf16_f32 v69, v10, v11
	v_cvt_pk_bf16_f32 v70, v12, v13
	v_cvt_pk_bf16_f32 v71, v14, v15
	v_mov_b32_dpp v72, v64 quad_perm:[1,0,3,2] row_mask:0xf bank_mask:0xf
	v_mov_b32_dpp v73, v65 quad_perm:[1,0,3,2] row_mask:0xf bank_mask:0xf
	v_mov_b32_dpp v74, v66 quad_perm:[1,0,3,2] row_mask:0xf bank_mask:0xf
	v_mov_b32_dpp v75, v67 quad_perm:[1,0,3,2] row_mask:0xf bank_mask:0xf
	v_mov_b32_dpp v76, v68 quad_perm:[1,0,3,2] row_mask:0xf bank_mask:0xf
	v_mov_b32_dpp v77, v69 quad_perm:[1,0,3,2] row_mask:0xf bank_mask:0xf
	v_mov_b32_dpp v78, v70 quad_perm:[1,0,3,2] row_mask:0xf bank_mask:0xf
	v_mov_b32_dpp v79, v71 quad_perm:[1,0,3,2] row_mask:0xf bank_mask:0xf
	v_perm_b32 v72, v72, v64, v120
	v_perm_b32 v73, v73, v65, v120
	v_perm_b32 v74, v74, v66, v120
	v_perm_b32 v75, v75, v67, v120
	v_perm_b32 v76, v76, v68, v120
	v_perm_b32 v77, v77, v69, v120
	v_perm_b32 v78, v78, v70, v120
	v_perm_b32 v79, v79, v71, v120
	ds_write_b32 v121, v72
	ds_write_b32 v121, v73 offset:128
	ds_write_b32 v121, v74 offset:512
	ds_write_b32 v121, v75 offset:640
	ds_write_b32 v121, v76 offset:1024
	ds_write_b32 v121, v77 offset:1152
	ds_write_b32 v121, v78 offset:1536
	ds_write_b32 v121, v79 offset:1664
	ds_read_b128 v[104:107], v113
	ds_read_b128 v[108:111], v113 offset:1024
	s_waitcnt lgkmcnt(0)
	global_store_dwordx4 v114, v[80:83], s[98:99]
	s_add_u32 s100, s98, 0x8000
	s_addc_u32 s101, s99, 0
	global_store_dwordx4 v114, v[84:87], s[100:101]
	global_store_dwordx4 v114, v[88:91], s[98:99] offset:64
	global_store_dwordx4 v114, v[92:95], s[100:101] offset:64
	s_add_u32 s98, s98, 0x10000
	s_addc_u32 s99, s99, 0
	global_store_dwordx4 v114, v[96:99], s[98:99]
	s_add_u32 s100, s98, 0x8000
	s_addc_u32 s101, s99, 0
	global_store_dwordx4 v114, v[100:103], s[100:101]
	global_store_dwordx4 v114, v[104:107], s[98:99] offset:64
	global_store_dwordx4 v114, v[108:111], s[100:101] offset:64
	s_branch .Lodin4_next
